# merged phases 2+3 (no SEAM2; carry flag + z-done counter) with S2 on WGs 64..191, PE on 0..63+192..255
# baseline (speedup 1.0000x reference)
.LBB0_267:
	v_add_u32_e32 v22, s27, v44
	ds_read2st64_b32 v[50:51], v22 offset1:1
	v_cvt_pk_bf16_f32 v49, v17, v20
	v_mul_f32_e32 v21, v5, v20
	v_mul_f32_e32 v20, v4, v20
	v_fma_f32 v21, v4, v17, -v21
	v_fmac_f32_e32 v20, v5, v17
	s_waitcnt lgkmcnt(0)
	v_add_f32_e32 v50, v50, v21
	v_add_f32_e32 v17, v20, v51
	ds_read2st64_b32 v[20:21], v22 offset0:2 offset1:3
	v_cvt_pk_bf16_f32 v51, v50, v17
	ds_write2st64_b32 v22, v49, v51 offset1:2
	v_mul_f32_e32 v49, v5, v17
	v_mul_f32_e32 v17, v4, v17
	v_fma_f32 v49, v4, v50, -v49
	v_fmac_f32_e32 v17, v5, v50
	s_waitcnt lgkmcnt(1)
	v_add_f32_e32 v49, v20, v49
	v_add_f32_e32 v17, v17, v21
	ds_read2st64_b32 v[20:21], v22 offset0:4 offset1:5
	v_cvt_pk_bf16_f32 v50, v49, v17
	v_mul_f32_e32 v51, v5, v17
	v_mul_f32_e32 v17, v4, v17
	v_fma_f32 v51, v4, v49, -v51
	v_fmac_f32_e32 v17, v5, v49
	s_waitcnt lgkmcnt(0)
	v_add_f32_e32 v51, v20, v51
	v_add_f32_e32 v17, v17, v21
	ds_read2st64_b32 v[20:21], v22 offset0:6 offset1:7
	v_cvt_pk_bf16_f32 v49, v51, v17
	ds_write2st64_b32 v22, v50, v49 offset0:4 offset1:6
	v_mul_f32_e32 v49, v5, v17
	v_mul_f32_e32 v17, v4, v17
	v_fma_f32 v49, v4, v51, -v49
	v_fmac_f32_e32 v17, v5, v51
	s_waitcnt lgkmcnt(1)
	v_add_f32_e32 v49, v20, v49
	v_add_f32_e32 v17, v17, v21
	ds_read2st64_b32 v[20:21], v22 offset0:8 offset1:9
	v_cvt_pk_bf16_f32 v50, v49, v17
	v_mul_f32_e32 v51, v5, v17
	v_mul_f32_e32 v17, v4, v17
	v_fma_f32 v51, v4, v49, -v51
	v_fmac_f32_e32 v17, v5, v49
	s_waitcnt lgkmcnt(0)
	v_add_f32_e32 v51, v20, v51
	v_add_f32_e32 v17, v17, v21
	ds_read2st64_b32 v[20:21], v22 offset0:10 offset1:11
	v_cvt_pk_bf16_f32 v49, v51, v17
	ds_write2st64_b32 v22, v50, v49 offset0:8 offset1:10
	v_mul_f32_e32 v49, v5, v17
	v_mul_f32_e32 v17, v4, v17
	v_fma_f32 v49, v4, v51, -v49
	v_fmac_f32_e32 v17, v5, v51
	s_waitcnt lgkmcnt(1)
	v_add_f32_e32 v49, v20, v49
	v_add_f32_e32 v17, v17, v21
	ds_read2st64_b32 v[20:21], v22 offset0:12 offset1:13
	v_cvt_pk_bf16_f32 v50, v49, v17
	v_mul_f32_e32 v51, v5, v17
	v_mul_f32_e32 v17, v4, v17
	v_fma_f32 v51, v4, v49, -v51
	v_fmac_f32_e32 v17, v5, v49
	s_waitcnt lgkmcnt(0)
	v_add_f32_e32 v51, v20, v51
	v_add_f32_e32 v49, v17, v21
	ds_read2st64_b32 v[20:21], v22 offset0:14 offset1:15
	v_cvt_pk_bf16_f32 v17, v51, v49
	ds_write2st64_b32 v22, v50, v17 offset0:12 offset1:14
	v_mul_f32_e32 v17, v5, v49
	v_fma_f32 v17, v4, v51, -v17
	s_waitcnt lgkmcnt(1)
	v_add_f32_e32 v17, v20, v17
	v_mul_f32_e32 v20, v4, v49
	v_fmac_f32_e32 v20, v5, v51
	s_addk_i32 s27, 0x1000
	v_add_f32_e32 v20, v20, v21
	s_cmpk_eq_i32 s27, 0x4000
	s_cbranch_scc0 .LBB0_267
	s_waitcnt lgkmcnt(0)
	s_barrier
	ds_read_b128 v[50:53], v45
	ds_read_b128 v[54:57], v45 offset:16
	v_mov_b64_e32 v[20:21], s[78:79]
	s_movk_i32 s27, 0x100
	s_waitcnt lgkmcnt(1)
	v_lshlrev_b32_e32 v17, 16, v51
	v_and_or_b32 v58, v50, s21, v17
	v_lshlrev_b32_e32 v17, 16, v53
	v_and_or_b32 v59, v52, s21, v17
	s_waitcnt lgkmcnt(0)
	v_lshlrev_b32_e32 v17, 16, v55
	v_and_or_b32 v60, v54, s21, v17
	v_lshlrev_b32_e32 v17, 16, v57
	v_and_or_b32 v61, v56, s21, v17
	v_lshrrev_b32_e32 v17, 16, v50
	v_and_or_b32 v50, v51, s24, v17
	v_lshrrev_b32_e32 v17, 16, v52
	v_and_or_b32 v51, v53, s24, v17
	v_lshrrev_b32_e32 v17, 16, v54
	v_and_or_b32 v52, v55, s24, v17
	v_lshrrev_b32_e32 v17, 16, v56
	v_and_or_b32 v53, v57, s24, v17
	v_or_b32_e32 v17, s58, v1
	v_mad_i64_i32 v[54:55], s[30:31], v17, s25, v[20:21]
	v_mov_b32_e32 v17, v3
	v_lshl_add_u64 v[54:55], v[54:55], 0, v[16:17]
	v_lshl_add_u64 v[56:57], v[54:55], 0, s[22:23]
	v_add_co_u32_e32 v54, vcc, s26, v54
	s_nop 1
	v_addc_co_u32_e32 v55, vcc, 0, v55, vcc
	global_store_dwordx4 v[54:55], v[58:61], off offset:1024 sc1
	global_store_dwordx4 v[56:57], v[50:53], off offset:128 sc1
	ds_read_b128 v[50:53], v46
	ds_read_b128 v[54:57], v46 offset:16
	s_waitcnt lgkmcnt(1)
	v_lshlrev_b32_e32 v22, 16, v51
	v_and_or_b32 v58, v50, s21, v22
	v_lshlrev_b32_e32 v22, 16, v53
	v_and_or_b32 v59, v52, s21, v22
	s_waitcnt lgkmcnt(0)
	v_lshlrev_b32_e32 v22, 16, v55
	v_and_or_b32 v60, v54, s21, v22
	v_lshlrev_b32_e32 v22, 16, v57
	v_and_or_b32 v61, v56, s21, v22
	v_lshrrev_b32_e32 v22, 16, v50
	v_and_or_b32 v50, v51, s24, v22
	v_lshrrev_b32_e32 v22, 16, v52
	v_and_or_b32 v51, v53, s24, v22
	v_lshrrev_b32_e32 v22, 16, v54
	v_and_or_b32 v52, v55, s24, v22
	v_lshrrev_b32_e32 v22, 16, v56
	v_and_or_b32 v53, v57, s24, v22
	v_or_b32_e32 v22, s58, v34
	v_mad_i64_i32 v[54:55], s[30:31], v22, s25, v[20:21]
	v_lshl_add_u64 v[54:55], v[54:55], 0, v[16:17]
	v_lshl_add_u64 v[56:57], v[54:55], 0, s[22:23]
	v_add_co_u32_e32 v54, vcc, s26, v54
	s_nop 1
	v_addc_co_u32_e32 v55, vcc, 0, v55, vcc
	global_store_dwordx4 v[54:55], v[58:61], off offset:1024 sc1
	global_store_dwordx4 v[56:57], v[50:53], off offset:128 sc1
	ds_read_b128 v[50:53], v47
	ds_read_b128 v[54:57], v47 offset:16
	s_waitcnt lgkmcnt(1)
	v_lshlrev_b32_e32 v22, 16, v51
	v_and_or_b32 v58, v50, s21, v22
	v_lshlrev_b32_e32 v22, 16, v53
	v_and_or_b32 v59, v52, s21, v22
	s_waitcnt lgkmcnt(0)
	v_lshlrev_b32_e32 v22, 16, v55
	v_and_or_b32 v60, v54, s21, v22
	v_lshlrev_b32_e32 v22, 16, v57
	v_and_or_b32 v61, v56, s21, v22
	v_lshrrev_b32_e32 v22, 16, v50
	v_and_or_b32 v50, v51, s24, v22
	v_lshrrev_b32_e32 v22, 16, v52
	v_and_or_b32 v51, v53, s24, v22
	v_lshrrev_b32_e32 v22, 16, v54
	v_and_or_b32 v52, v55, s24, v22
	v_lshrrev_b32_e32 v22, 16, v56
	v_and_or_b32 v53, v57, s24, v22
	v_or_b32_e32 v22, s58, v35
	v_mad_i64_i32 v[54:55], s[30:31], v22, s25, v[20:21]
	v_lshl_add_u64 v[54:55], v[54:55], 0, v[16:17]
	v_lshl_add_u64 v[56:57], v[54:55], 0, s[22:23]
	v_add_co_u32_e32 v54, vcc, s26, v54
	s_nop 1
	v_addc_co_u32_e32 v55, vcc, 0, v55, vcc
	global_store_dwordx4 v[54:55], v[58:61], off offset:1024 sc1
	global_store_dwordx4 v[56:57], v[50:53], off offset:128 sc1
	ds_read_b128 v[50:53], v48
	ds_read_b128 v[54:57], v48 offset:16
	s_waitcnt lgkmcnt(1)
	v_lshlrev_b32_e32 v22, 16, v51
	v_and_or_b32 v58, v50, s21, v22
	v_lshlrev_b32_e32 v22, 16, v53
	v_and_or_b32 v59, v52, s21, v22
	s_waitcnt lgkmcnt(0)
	v_lshlrev_b32_e32 v22, 16, v55
	v_and_or_b32 v60, v54, s21, v22
	v_lshlrev_b32_e32 v22, 16, v57
	v_and_or_b32 v61, v56, s21, v22
	v_lshrrev_b32_e32 v22, 16, v50
	v_and_or_b32 v50, v51, s24, v22
	v_lshrrev_b32_e32 v22, 16, v52
	v_and_or_b32 v51, v53, s24, v22
	v_lshrrev_b32_e32 v22, 16, v54
	v_and_or_b32 v52, v55, s24, v22
	v_lshrrev_b32_e32 v22, 16, v56
	v_and_or_b32 v53, v57, s24, v22
	v_add_u32_e32 v22, s58, v36
	v_mad_i64_i32 v[20:21], s[30:31], v22, s25, v[20:21]
	v_lshl_add_u64 v[20:21], v[20:21], 0, v[16:17]
	v_lshl_add_u64 v[54:55], v[20:21], 0, s[22:23]
	v_add_co_u32_e32 v20, vcc, 0x3a00000, v20
	s_mov_b64 s[58:59], 0
	s_nop 0
	v_addc_co_u32_e32 v21, vcc, 0, v21, vcc
	s_and_b64 vcc, exec, s[56:57]
	global_store_dwordx4 v[20:21], v[58:61], off offset:1024 sc1
	global_store_dwordx4 v[54:55], v[50:53], off offset:128 sc1
	s_barrier
	s_cbranch_vccz .LBB0_264
	s_waitcnt vmcnt(0)
	s_barrier
	v_and_b32_e32 v1, 0x3ff, v0
	v_cmp_eq_u32_e32 vcc, 0, v1
	s_and_saveexec_b64 s[4:5], vcc
	s_cbranch_execz .Lmg_c1
	s_lshl_b32 s6, s96, 2
	s_and_b32 s6, s6, 28
	s_bfe_u32 s7, s96, 0x20004
	s_or_b32 s6, s6, s7
	s_lshl_b32 s6, s6, 8
	s_add_u32 s6, s78, s6
	s_addc_u32 s7, s79, 0
	v_mov_b32_e32 v1, 0xe814000
	v_mov_b32_e32 v2, 1
	global_atomic_add v1, v2, s[6:7]
.Lmg_c1:
	s_or_b64 exec, exec, s[4:5]
.LBB0_269:
	s_xor_b64 s[0:1], s[52:53], -1
	s_and_b64 s[0:1], s[54:55], s[0:1]
	v_readlane_b32 s26, v254, 38
	s_and_b64 vcc, exec, s[0:1]
	v_readlane_b32 s27, v254, 39
	s_cbranch_vccnz .LBB0_364
	s_sub_i32 s25, s96, s2
	v_and_b32_e32 v1, 0x3ff, v0
	v_lshl_or_b32 v46, s25, 9, v1
	s_mov_b32 s0, 0x20000
	v_writelane_b32 v254, s36, 40
	s_sub_i32 s24, s3, s2
	v_cmp_gt_i32_e32 vcc, s0, v46
	v_writelane_b32 v254, s37, 41
	s_and_saveexec_b64 s[0:1], vcc
	s_cbranch_execz .LBB0_275
	s_add_u32 s4, s78, 0x6600000
	s_addc_u32 s5, s79, 0
	s_add_u32 s6, s78, 0xc600000
	v_readlane_b32 s36, v254, 21
	s_addc_u32 s7, s79, 0
	s_lshl_b32 s16, s24, 9
	v_readlane_b32 s50, v254, 35
	v_readlane_b32 s51, v254, 36
	s_add_u32 s8, s50, 0x1000
	s_addc_u32 s9, s51, 0
	s_add_u32 s10, s50, 0x2000
	s_addc_u32 s11, s51, 0
	s_lshl_b32 s12, s3, 12
	s_lshl_b32 s2, s2, 12
	v_lshlrev_b32_e32 v47, 3, v46
	s_sub_i32 s2, s12, s2
	s_mov_b64 s[12:13], 0
	v_mov_b32_e32 v27, 0
	s_mov_b32 s17, 0x1ffff
	v_readlane_b32 s37, v254, 22
	v_readlane_b32 s38, v254, 23
	v_readlane_b32 s39, v254, 24
	v_readlane_b32 s40, v254, 25
	v_readlane_b32 s41, v254, 26
	v_readlane_b32 s42, v254, 27
	v_readlane_b32 s43, v254, 28
	v_readlane_b32 s44, v254, 29
	v_readlane_b32 s45, v254, 30
	v_readlane_b32 s46, v254, 31
	v_readlane_b32 s47, v254, 32
	v_readlane_b32 s48, v254, 33
	v_readlane_b32 s49, v254, 34
	s_branch .LBB0_273

.LBB0_278:
	s_cmpk_lt_i32 s25, 0x200
	s_movk_i32 s4, 0x540
	s_cselect_b32 s26, s4, 0xf0
	s_add_i32 s26, s26, s25
	s_cmpk_gt_i32 s26, 0x7f
	s_mov_b64 s[4:5], -1
	s_cbranch_scc0 .LBB0_293
	s_cmpk_gt_u32 s26, 0x33f
	s_cbranch_scc0 .LBB0_285
	s_cmpk_gt_u32 s26, 0x53f
	s_cbranch_scc0 .LBB0_282
	s_add_i32 s50, s26, 0xfffffac0
	s_lshl_b64 s[4:5], s[50:51], 13
	v_readlane_b32 s80, v254, 5
	v_mov_b32_e32 v19, s5
	v_or_b32_e32 v18, s4, v70
	v_readlane_b32 s82, v254, 7
	v_readlane_b32 s83, v254, 8
	s_mov_b64 s[4:5], 0x4000
	v_readlane_b32 s81, v254, 6
	v_lshl_add_u64 v[10:11], v[18:19], 2, s[82:83]
	global_load_dwordx4 v[2:5], v[10:11], off offset:16
	global_load_dwordx4 v[6:9], v[10:11], off
	v_lshl_add_u64 v[14:15], v[10:11], 0, s[4:5]
	v_add_co_u32_e32 v10, vcc, 0x4000, v10
	v_lshl_add_u64 v[18:19], v[18:19], 1, s[10:11]
	s_nop 0
	v_addc_co_u32_e32 v11, vcc, 0, v11, vcc
	global_load_dwordx4 v[10:13], v[10:11], off
	s_nop 0
	global_load_dwordx4 v[14:17], v[14:15], off offset:16
	v_readlane_b32 s84, v254, 9
	v_readlane_b32 s85, v254, 10
	v_readlane_b32 s86, v254, 11
	v_readlane_b32 s87, v254, 12
	v_readlane_b32 s88, v254, 13
	v_readlane_b32 s89, v254, 14
	v_readlane_b32 s90, v254, 15
	v_readlane_b32 s91, v254, 16
	v_readlane_b32 s92, v254, 17
	v_readlane_b32 s93, v254, 18
	v_readlane_b32 s94, v254, 19
	v_readlane_b32 s95, v254, 20
	s_mov_b64 s[4:5], 0
	s_waitcnt vmcnt(0)
	v_cvt_pk_bf16_f32 v6, v6, v7
	v_cvt_pk_bf16_f32 v7, v8, v9
	v_cvt_pk_bf16_f32 v8, v2, v3
	v_cvt_pk_bf16_f32 v9, v4, v5
	global_store_dwordx4 v[18:19], v[6:9], off sc1
	v_cvt_pk_bf16_f32 v2, v10, v11
	s_nop 0
	v_add_co_u32_e32 v6, vcc, 0x2000, v18
	v_cvt_pk_bf16_f32 v3, v12, v13
	v_cvt_pk_bf16_f32 v4, v14, v15
	v_cvt_pk_bf16_f32 v5, v16, v17
	v_addc_co_u32_e32 v7, vcc, 0, v19, vcc
	global_store_dwordx4 v[6:7], v[2:5], off sc1
.LBB0_282:
	s_andn2_b64 vcc, exec, s[4:5]
	s_cbranch_vccnz .LBB0_284
	v_lshl_add_u32 v72, s26, 5, v71
	v_lshlrev_b64 v[2:3], 12, v[72:73]
	v_lshl_add_u64 v[2:3], v[74:75], 0, v[2:3]
	global_load_dwordx4 v[46:49], v[2:3], off
	global_load_dwordx4 v[30:33], v[2:3], off offset:1024
	global_load_dwordx4 v[18:21], v[2:3], off offset:2048
	global_load_dwordx4 v[14:17], v[2:3], off offset:3072
	v_or_b32_e32 v86, 1, v72
	v_mov_b32_e32 v87, v73
	v_lshlrev_b64 v[2:3], 12, v[86:87]
	v_lshl_add_u64 v[2:3], v[74:75], 0, v[2:3]
	global_load_dwordx4 v[54:57], v[2:3], off
	global_load_dwordx4 v[34:37], v[2:3], off offset:1024
	global_load_dwordx4 v[22:25], v[2:3], off offset:2048
	global_load_dwordx4 v[10:13], v[2:3], off offset:3072
	v_and_b32_e32 v66, 64, v123
	v_add_u32_e32 v94, 64, v66
	v_or_b32_e32 v88, 2, v72
	v_mov_b32_e32 v89, v73
	v_lshlrev_b64 v[2:3], 12, v[88:89]
	v_lshl_add_u64 v[2:3], v[74:75], 0, v[2:3]
	global_load_dwordx4 v[58:61], v[2:3], off
	global_load_dwordx4 v[42:45], v[2:3], off offset:1024
	global_load_dwordx4 v[26:29], v[2:3], off offset:2048
	s_nop 0
	global_load_dwordx4 v[2:5], v[2:3], off offset:3072
	v_or_b32_e32 v90, 3, v72
	v_mov_b32_e32 v91, v73
	v_lshlrev_b64 v[6:7], 12, v[90:91]
	v_lshl_add_u64 v[6:7], v[74:75], 0, v[6:7]
	global_load_dwordx4 v[62:65], v[6:7], off
	global_load_dwordx4 v[50:53], v[6:7], off offset:1024
	global_load_dwordx4 v[38:41], v[6:7], off offset:2048
	s_nop 0
	global_load_dwordx4 v[6:9], v[6:7], off offset:3072
	s_mov_b32 s4, 0x358637bd
	s_waitcnt vmcnt(0)
	v_pk_mul_f32 v[66:67], v[48:49], v[48:49]
	v_pk_mul_f32 v[68:69], v[46:47], v[46:47]
	v_mul_f32_e32 v83, v14, v14
	v_pk_mov_b32 v[128:129], v[68:69], v[66:67] op_sel:[1,0]
	v_mov_b32_e32 v69, v67
	v_pk_add_f32 v[66:67], v[128:129], v[68:69]
	v_pk_mul_f32 v[68:69], v[32:33], v[32:33]
	v_pk_mul_f32 v[128:129], v[30:31], v[30:31]
	v_mul_f32_e32 v85, v15, v15
	v_pk_mov_b32 v[130:131], v[128:129], v[68:69] op_sel:[1,0]
	v_mov_b32_e32 v129, v69
	v_pk_add_f32 v[68:69], v[130:131], v[128:129]
	v_pk_add_f32 v[66:67], v[66:67], v[66:67] op_sel:[0,1] op_sel_hi:[1,0]
	v_pk_add_f32 v[68:69], v[68:69], v[68:69] op_sel:[0,1] op_sel_hi:[1,0]
	v_mov_b32_e32 v67, v83
	v_mov_b32_e32 v69, v85
	v_pk_add_f32 v[66:67], v[66:67], v[68:69]
	v_mul_f32_e32 v68, v19, v19
	v_mul_f32_e32 v92, v16, v16
	v_pk_fma_f32 v[68:69], v[18:19], v[18:19], v[68:69] op_sel_hi:[1,1,0]
	v_mul_f32_e32 v96, v17, v17
	v_mov_b32_e32 v69, v92
	v_mul_f32_e32 v92, v21, v21
	v_pk_fma_f32 v[128:129], v[20:21], v[20:21], v[92:93] op_sel_hi:[1,1,0]
	v_xor_b32_e32 v83, 8, v123
	v_mov_b32_e32 v129, v96
	v_pk_add_f32 v[68:69], v[68:69], v[128:129]
	v_xor_b32_e32 v85, 4, v123
	v_pk_add_f32 v[66:67], v[66:67], v[68:69]
	v_xor_b32_e32 v68, 32, v123
	v_cmp_lt_i32_e32 vcc, v68, v94
	v_xor_b32_e32 v69, 16, v123
	v_xor_b32_e32 v92, 2, v123
	v_cndmask_b32_e32 v68, v123, v68, vcc
	v_cmp_lt_i32_e32 vcc, v69, v94
	v_pk_mul_f32 v[128:129], v[56:57], v[56:57]
	v_pk_mul_f32 v[130:131], v[54:55], v[54:55]
	v_cndmask_b32_e32 v69, v123, v69, vcc
	v_cmp_lt_i32_e32 vcc, v83, v94
	v_pk_mov_b32 v[132:133], v[130:131], v[128:129] op_sel:[1,0]
	v_mov_b32_e32 v131, v129
	v_cndmask_b32_e32 v83, v123, v83, vcc
	v_cmp_lt_i32_e32 vcc, v85, v94
	v_pk_add_f32 v[128:129], v[132:133], v[130:131]
	v_pk_mul_f32 v[130:131], v[36:37], v[36:37]
	v_cndmask_b32_e32 v85, v123, v85, vcc
	v_cmp_lt_i32_e32 vcc, v92, v94
	v_pk_mul_f32 v[132:133], v[34:35], v[34:35]
	v_pk_add_f32 v[128:129], v[128:129], v[128:129] op_sel:[0,1] op_sel_hi:[1,0]
	v_cndmask_b32_e32 v92, v123, v92, vcc
	v_lshlrev_b32_e32 v96, 2, v92
	v_xor_b32_e32 v92, 1, v123
	v_cmp_lt_i32_e32 vcc, v92, v94
	v_pk_mov_b32 v[134:135], v[132:133], v[130:131] op_sel:[1,0]
	v_mov_b32_e32 v133, v131
	v_cndmask_b32_e32 v92, v123, v92, vcc
	v_pk_add_f32 v[130:131], v[134:135], v[132:133]
	v_lshlrev_b32_e32 v98, 2, v92
	v_mul_f32_e32 v92, v10, v10
	v_mul_f32_e32 v94, v11, v11
	v_pk_add_f32 v[130:131], v[130:131], v[130:131] op_sel:[0,1] op_sel_hi:[1,0]
	v_mov_b32_e32 v129, v92
	v_mov_b32_e32 v131, v94
	v_mul_f32_e32 v92, v23, v23
	v_mul_f32_e32 v132, v12, v12
	v_pk_add_f32 v[128:129], v[128:129], v[130:131]
	v_pk_fma_f32 v[130:131], v[22:23], v[22:23], v[92:93] op_sel_hi:[1,1,0]
	v_mul_f32_e32 v92, v25, v25
	v_mul_f32_e32 v134, v13, v13
	v_mov_b32_e32 v131, v132
	v_pk_fma_f32 v[132:133], v[24:25], v[24:25], v[92:93] op_sel_hi:[1,1,0]
	v_lshlrev_b32_e32 v68, 2, v68
	v_mov_b32_e32 v133, v134
	v_pk_add_f32 v[130:131], v[130:131], v[132:133]
	v_lshlrev_b32_e32 v69, 2, v69
	v_pk_add_f32 v[128:129], v[128:129], v[130:131]
	v_mov_b32_e32 v131, v66
	v_mov_b32_e32 v130, v128
	v_mov_b32_e32 v66, v129
	v_pk_add_f32 v[66:67], v[130:131], v[66:67]
	ds_bpermute_b32 v129, v68, v67
	ds_bpermute_b32 v128, v68, v66
	v_lshlrev_b32_e32 v83, 2, v83
	v_lshlrev_b32_e32 v85, 2, v85
	v_pk_mul_f32 v[130:131], v[58:59], v[58:59]
	s_waitcnt lgkmcnt(0)
	v_pk_add_f32 v[66:67], v[66:67], v[128:129]
	ds_bpermute_b32 v129, v69, v67
	ds_bpermute_b32 v128, v69, v66
	s_waitcnt lgkmcnt(0)
	v_pk_add_f32 v[66:67], v[66:67], v[128:129]
	ds_bpermute_b32 v129, v83, v67
	ds_bpermute_b32 v128, v83, v66
	s_waitcnt lgkmcnt(0)
	v_pk_add_f32 v[66:67], v[66:67], v[128:129]
	ds_bpermute_b32 v129, v85, v67
	ds_bpermute_b32 v128, v85, v66
	s_waitcnt lgkmcnt(0)
	v_pk_add_f32 v[66:67], v[66:67], v[128:129]
	ds_bpermute_b32 v129, v96, v67
	ds_bpermute_b32 v128, v96, v66
	s_waitcnt lgkmcnt(0)
	v_pk_add_f32 v[66:67], v[66:67], v[128:129]
	ds_bpermute_b32 v129, v98, v67
	ds_bpermute_b32 v128, v98, v66
	s_waitcnt lgkmcnt(0)
	v_pk_add_f32 v[66:67], v[66:67], v[128:129]
	v_mov_b64_e32 v[128:129], s[4:5]
	v_pk_fma_f32 v[66:67], v[66:67], s[56:57], v[128:129] op_sel_hi:[1,0,0]
	s_nop 0
	v_mul_f32_e32 v92, 0x4b800000, v67
	v_cmp_gt_f32_e64 s[4:5], s57, v67
	v_cmp_gt_f32_e32 vcc, s57, v66
	s_nop 0
	v_cndmask_b32_e64 v67, v67, v92, s[4:5]
	v_rsq_f32_e32 v67, v67
	s_nop 0
	v_mul_f32_e32 v92, 0x45800000, v67
	v_cndmask_b32_e64 v94, v67, v92, s[4:5]
	v_mul_f32_e32 v67, 0x4b800000, v66
	v_cndmask_b32_e32 v66, v66, v67, vcc
	v_rsq_f32_e32 v66, v66
	v_pk_mul_f32 v[46:47], v[46:47], v[94:95] op_sel_hi:[1,0]
	v_pk_mul_f32 v[48:49], v[48:49], v[94:95] op_sel_hi:[1,0]
	v_pk_mul_f32 v[30:31], v[30:31], v[94:95] op_sel_hi:[1,0]
	v_mul_f32_e32 v67, 0x45800000, v66
	v_cndmask_b32_e32 v92, v66, v67, vcc
	v_pk_mul_f32 v[66:67], v[60:61], v[60:61]
	v_pk_mul_f32 v[32:33], v[32:33], v[94:95] op_sel_hi:[1,0]
	v_pk_mov_b32 v[132:133], v[130:131], v[66:67] op_sel:[1,0]
	v_mov_b32_e32 v131, v67
	v_pk_add_f32 v[66:67], v[132:133], v[130:131]
	v_pk_mul_f32 v[130:131], v[44:45], v[44:45]
	v_pk_mul_f32 v[132:133], v[42:43], v[42:43]
	v_pk_add_f32 v[66:67], v[66:67], v[66:67] op_sel:[0,1] op_sel_hi:[1,0]
	v_pk_mov_b32 v[134:135], v[132:133], v[130:131] op_sel:[1,0]
	v_mov_b32_e32 v133, v131
	v_pk_add_f32 v[130:131], v[134:135], v[132:133]
	v_mul_f32_e32 v132, v2, v2
	v_mul_f32_e32 v133, v3, v3
	v_pk_add_f32 v[130:131], v[130:131], v[130:131] op_sel:[0,1] op_sel_hi:[1,0]
	v_mov_b32_e32 v67, v132
	v_mov_b32_e32 v131, v133
	v_pk_add_f32 v[66:67], v[66:67], v[130:131]
	v_mul_f32_e32 v130, v27, v27
	v_mul_f32_e32 v132, v29, v29
	v_mul_f32_e32 v134, v4, v4
	v_mul_f32_e32 v135, v5, v5
	v_pk_fma_f32 v[130:131], v[26:27], v[26:27], v[130:131] op_sel_hi:[1,1,0]
	v_pk_fma_f32 v[132:133], v[28:29], v[28:29], v[132:133] op_sel_hi:[1,1,0]
	v_mov_b32_e32 v131, v134
	v_mov_b32_e32 v133, v135
	v_pk_add_f32 v[130:131], v[130:131], v[132:133]
	v_pk_mul_f32 v[132:133], v[62:63], v[62:63]
	v_pk_add_f32 v[66:67], v[66:67], v[130:131]
	v_pk_mul_f32 v[130:131], v[64:65], v[64:65]
	v_pk_mul_f32 v[18:19], v[18:19], v[94:95] op_sel_hi:[1,0]
	v_pk_mov_b32 v[134:135], v[132:133], v[130:131] op_sel:[1,0]
	v_mov_b32_e32 v133, v131
	v_pk_add_f32 v[130:131], v[134:135], v[132:133]
	v_pk_mul_f32 v[132:133], v[52:53], v[52:53]
	v_pk_mul_f32 v[134:135], v[50:51], v[50:51]
	v_pk_add_f32 v[130:131], v[130:131], v[130:131] op_sel:[0,1] op_sel_hi:[1,0]
	v_pk_mov_b32 v[136:137], v[134:135], v[132:133] op_sel:[1,0]
	v_mov_b32_e32 v135, v133
	v_pk_add_f32 v[132:133], v[136:137], v[134:135]
	v_mul_f32_e32 v134, v6, v6
	v_mul_f32_e32 v135, v7, v7
	v_pk_add_f32 v[132:133], v[132:133], v[132:133] op_sel:[0,1] op_sel_hi:[1,0]
	v_mov_b32_e32 v131, v134
	v_mov_b32_e32 v133, v135
	v_pk_add_f32 v[130:131], v[130:131], v[132:133]
	v_mul_f32_e32 v132, v39, v39
	v_mul_f32_e32 v134, v41, v41
	v_mul_f32_e32 v136, v8, v8
	v_mul_f32_e32 v137, v9, v9
	v_pk_fma_f32 v[132:133], v[38:39], v[38:39], v[132:133] op_sel_hi:[1,1,0]
	v_pk_fma_f32 v[134:135], v[40:41], v[40:41], v[134:135] op_sel_hi:[1,1,0]
	v_mov_b32_e32 v133, v136
	v_mov_b32_e32 v135, v137
	v_pk_add_f32 v[132:133], v[132:133], v[134:135]
	v_pk_mul_f32 v[20:21], v[20:21], v[94:95] op_sel_hi:[1,0]
	v_pk_add_f32 v[130:131], v[130:131], v[132:133]
	v_mov_b32_e32 v133, v66
	v_mov_b32_e32 v132, v130
	v_mov_b32_e32 v66, v131
	v_pk_add_f32 v[66:67], v[132:133], v[66:67]
	ds_bpermute_b32 v131, v68, v67
	ds_bpermute_b32 v130, v68, v66
	v_pk_mul_f32 v[14:15], v[14:15], v[94:95] op_sel_hi:[1,0]
	v_pk_mul_f32 v[16:17], v[16:17], v[94:95] op_sel_hi:[1,0]
	v_pk_mul_f32 v[10:11], v[10:11], v[92:93] op_sel_hi:[1,0]
	v_pk_mul_f32 v[12:13], v[12:13], v[92:93] op_sel_hi:[1,0]
	s_waitcnt lgkmcnt(0)
	v_pk_add_f32 v[66:67], v[66:67], v[130:131]
	ds_bpermute_b32 v131, v69, v67
	ds_bpermute_b32 v130, v69, v66
	s_waitcnt lgkmcnt(0)
	v_pk_add_f32 v[66:67], v[66:67], v[130:131]
	ds_bpermute_b32 v69, v83, v67
	ds_bpermute_b32 v68, v83, v66
	s_waitcnt lgkmcnt(0)
	v_pk_add_f32 v[66:67], v[66:67], v[68:69]
	ds_bpermute_b32 v69, v85, v67
	ds_bpermute_b32 v68, v85, v66
	s_waitcnt lgkmcnt(0)
	v_pk_add_f32 v[66:67], v[66:67], v[68:69]
	ds_bpermute_b32 v69, v96, v67
	ds_bpermute_b32 v68, v96, v66
	s_waitcnt lgkmcnt(0)
	v_pk_add_f32 v[66:67], v[66:67], v[68:69]
	ds_bpermute_b32 v69, v98, v67
	ds_bpermute_b32 v68, v98, v66
	s_waitcnt lgkmcnt(0)
	v_pk_add_f32 v[66:67], v[66:67], v[68:69]
	s_nop 0
	v_pk_fma_f32 v[66:67], v[66:67], s[56:57], v[128:129] op_sel_hi:[1,0,0]
	s_nop 0
	v_mul_f32_e32 v68, 0x4b800000, v67
	v_cmp_gt_f32_e64 s[4:5], s57, v67
	v_cmp_gt_f32_e32 vcc, s57, v66
	s_nop 0
	v_cndmask_b32_e64 v67, v67, v68, s[4:5]
	v_rsq_f32_e32 v67, v67
	s_nop 0
	v_mul_f32_e32 v68, 0x45800000, v67
	v_cndmask_b32_e64 v98, v67, v68, s[4:5]
	v_mul_f32_e32 v67, 0x4b800000, v66
	v_cndmask_b32_e32 v66, v66, v67, vcc
	v_rsq_f32_e32 v66, v66
	v_pk_mul_f32 v[2:3], v[2:3], v[98:99] op_sel_hi:[1,0]
	v_pk_mul_f32 v[4:5], v[4:5], v[98:99] op_sel_hi:[1,0]
	v_mul_f32_e32 v67, 0x45800000, v66
	v_cndmask_b32_e32 v96, v66, v67, vcc
	global_load_dwordx4 v[66:69], v[76:77], off
	s_waitcnt vmcnt(0)
	v_pk_mul_f32 v[48:49], v[48:49], v[68:69]
	v_pk_mul_f32 v[46:47], v[46:47], v[66:67]
	s_nop 0
	v_cvt_pk_bf16_f32 v46, v46, v47
	v_cvt_pk_bf16_f32 v47, v48, v49
	v_lshlrev_b64 v[48:49], 11, v[72:73]
	v_lshl_add_u64 v[128:129], v[80:81], 0, v[48:49]
	global_store_dwordx2 v[128:129], v[46:47], off sc1
	v_pk_mul_f32 v[46:47], v[54:55], v[92:93] op_sel_hi:[1,0]
	v_pk_mul_f32 v[48:49], v[56:57], v[92:93] op_sel_hi:[1,0]
	v_pk_mul_f32 v[46:47], v[46:47], v[66:67]
	v_pk_mul_f32 v[48:49], v[48:49], v[68:69]
	v_cvt_pk_bf16_f32 v46, v46, v47
	v_cvt_pk_bf16_f32 v47, v48, v49
	v_lshlrev_b64 v[48:49], 11, v[86:87]
	v_lshl_add_u64 v[54:55], v[80:81], 0, v[48:49]
	global_store_dwordx2 v[54:55], v[46:47], off sc1
	v_pk_mul_f32 v[46:47], v[58:59], v[98:99] op_sel_hi:[1,0]
	v_pk_mul_f32 v[48:49], v[60:61], v[98:99] op_sel_hi:[1,0]
	v_pk_mul_f32 v[46:47], v[66:67], v[46:47]
	v_pk_mul_f32 v[48:49], v[68:69], v[48:49]
	v_cvt_pk_bf16_f32 v46, v46, v47
	v_cvt_pk_bf16_f32 v47, v48, v49
	v_lshlrev_b64 v[48:49], 11, v[88:89]
	v_lshl_add_u64 v[56:57], v[80:81], 0, v[48:49]
	global_store_dwordx2 v[56:57], v[46:47], off sc1
	v_pk_mul_f32 v[46:47], v[62:63], v[96:97] op_sel_hi:[1,0]
	v_pk_mul_f32 v[48:49], v[64:65], v[96:97] op_sel_hi:[1,0]
	v_pk_mul_f32 v[46:47], v[66:67], v[46:47]
	v_pk_mul_f32 v[48:49], v[68:69], v[48:49]
	v_cvt_pk_bf16_f32 v46, v46, v47
	v_cvt_pk_bf16_f32 v47, v48, v49
	v_lshlrev_b64 v[48:49], 11, v[90:91]
	v_lshl_add_u64 v[58:59], v[80:81], 0, v[48:49]
	global_store_dwordx2 v[58:59], v[46:47], off sc1
	global_load_dwordx4 v[46:49], v[76:77], off offset:1024
	s_waitcnt vmcnt(0)
	v_pk_mul_f32 v[32:33], v[32:33], v[48:49]
	v_pk_mul_f32 v[30:31], v[30:31], v[46:47]
	s_nop 0
	v_cvt_pk_bf16_f32 v30, v30, v31
	v_cvt_pk_bf16_f32 v31, v32, v33
	global_store_dwordx2 v[128:129], v[30:31], off offset:512 sc1
	v_pk_mul_f32 v[30:31], v[34:35], v[92:93] op_sel_hi:[1,0]
	v_pk_mul_f32 v[32:33], v[36:37], v[92:93] op_sel_hi:[1,0]
	v_pk_mul_f32 v[30:31], v[30:31], v[46:47]
	v_pk_mul_f32 v[32:33], v[32:33], v[48:49]
	v_cvt_pk_bf16_f32 v30, v30, v31
	v_cvt_pk_bf16_f32 v31, v32, v33
	global_store_dwordx2 v[54:55], v[30:31], off offset:512 sc1
	v_pk_mul_f32 v[30:31], v[42:43], v[98:99] op_sel_hi:[1,0]
	v_pk_mul_f32 v[32:33], v[44:45], v[98:99] op_sel_hi:[1,0]
	v_pk_mul_f32 v[30:31], v[46:47], v[30:31]
	v_pk_mul_f32 v[32:33], v[48:49], v[32:33]
	v_cvt_pk_bf16_f32 v30, v30, v31
	v_cvt_pk_bf16_f32 v31, v32, v33
	global_store_dwordx2 v[56:57], v[30:31], off offset:512 sc1
	v_pk_mul_f32 v[30:31], v[50:51], v[96:97] op_sel_hi:[1,0]
	v_pk_mul_f32 v[32:33], v[52:53], v[96:97] op_sel_hi:[1,0]
	v_pk_mul_f32 v[30:31], v[46:47], v[30:31]
	v_pk_mul_f32 v[32:33], v[48:49], v[32:33]
	v_cvt_pk_bf16_f32 v30, v30, v31
	v_cvt_pk_bf16_f32 v31, v32, v33
	global_store_dwordx2 v[58:59], v[30:31], off offset:512 sc1
	global_load_dwordx4 v[30:33], v[76:77], off offset:2048
	s_waitcnt vmcnt(0)
	v_pk_mul_f32 v[20:21], v[20:21], v[32:33]
	v_pk_mul_f32 v[18:19], v[18:19], v[30:31]
	s_nop 0
	v_cvt_pk_bf16_f32 v18, v18, v19
	v_cvt_pk_bf16_f32 v19, v20, v21
	global_store_dwordx2 v[128:129], v[18:19], off offset:1024 sc1
	v_pk_mul_f32 v[18:19], v[22:23], v[92:93] op_sel_hi:[1,0]
	v_pk_mul_f32 v[20:21], v[24:25], v[92:93] op_sel_hi:[1,0]
	v_pk_mul_f32 v[18:19], v[18:19], v[30:31]
	v_pk_mul_f32 v[20:21], v[20:21], v[32:33]
	v_cvt_pk_bf16_f32 v18, v18, v19
	v_cvt_pk_bf16_f32 v19, v20, v21
	global_store_dwordx2 v[54:55], v[18:19], off offset:1024 sc1
	v_pk_mul_f32 v[18:19], v[26:27], v[98:99] op_sel_hi:[1,0]
	v_pk_mul_f32 v[20:21], v[28:29], v[98:99] op_sel_hi:[1,0]
	v_pk_mul_f32 v[18:19], v[18:19], v[30:31]
	v_pk_mul_f32 v[20:21], v[20:21], v[32:33]
	v_cvt_pk_bf16_f32 v18, v18, v19
	v_cvt_pk_bf16_f32 v19, v20, v21
	global_store_dwordx2 v[56:57], v[18:19], off offset:1024 sc1
	v_pk_mul_f32 v[18:19], v[38:39], v[96:97] op_sel_hi:[1,0]
	v_pk_mul_f32 v[20:21], v[40:41], v[96:97] op_sel_hi:[1,0]
	v_pk_mul_f32 v[18:19], v[30:31], v[18:19]
	v_pk_mul_f32 v[20:21], v[32:33], v[20:21]
	v_cvt_pk_bf16_f32 v18, v18, v19
	v_cvt_pk_bf16_f32 v19, v20, v21
	global_store_dwordx2 v[58:59], v[18:19], off offset:1024 sc1
	global_load_dwordx4 v[18:21], v[76:77], off offset:3072
	s_waitcnt vmcnt(0)
	v_pk_mul_f32 v[4:5], v[4:5], v[20:21]
	v_pk_mul_f32 v[2:3], v[2:3], v[18:19]
	v_pk_mul_f32 v[16:17], v[16:17], v[20:21]
	v_cvt_pk_bf16_f32 v2, v2, v3
	v_cvt_pk_bf16_f32 v3, v4, v5
	global_store_dwordx2 v[56:57], v[2:3], off offset:1536 sc1
	v_pk_mul_f32 v[2:3], v[6:7], v[96:97] op_sel_hi:[1,0]
	v_pk_mul_f32 v[4:5], v[8:9], v[96:97] op_sel_hi:[1,0]
	v_pk_mul_f32 v[14:15], v[14:15], v[18:19]
	v_pk_mul_f32 v[12:13], v[12:13], v[20:21]
	v_pk_mul_f32 v[10:11], v[10:11], v[18:19]
	v_pk_mul_f32 v[4:5], v[4:5], v[20:21]
	v_pk_mul_f32 v[2:3], v[2:3], v[18:19]
	v_cvt_pk_bf16_f32 v14, v14, v15
	v_cvt_pk_bf16_f32 v15, v16, v17
	v_cvt_pk_bf16_f32 v10, v10, v11
	v_cvt_pk_bf16_f32 v11, v12, v13
	v_cvt_pk_bf16_f32 v2, v2, v3
	v_cvt_pk_bf16_f32 v3, v4, v5
	global_store_dwordx2 v[128:129], v[14:15], off offset:1536 sc1
	global_store_dwordx2 v[54:55], v[10:11], off offset:1536 sc1
	global_store_dwordx2 v[58:59], v[2:3], off offset:1536 sc1

.LBB0_326:
	global_load_dword v4, v[2:3], off
	v_lshl_add_u64 v[2:3], v[2:3], 0, s[50:51]
	global_load_dword v5, v[2:3], off
	v_lshl_add_u64 v[2:3], v[2:3], 0, s[50:51]
	global_load_dword v6, v[2:3], off
	v_lshl_add_u64 v[2:3], v[2:3], 0, s[50:51]
	global_load_dword v7, v[2:3], off
	v_lshl_add_u64 v[2:3], v[2:3], 0, s[50:51]
	global_load_dword v8, v[2:3], off
	v_lshl_add_u64 v[2:3], v[2:3], 0, s[50:51]
	global_load_dword v9, v[2:3], off
	v_lshl_add_u64 v[2:3], v[2:3], 0, s[50:51]
	global_load_dword v10, v[2:3], off
	v_lshl_add_u64 v[2:3], v[2:3], 0, s[50:51]
	global_load_dword v11, v[2:3], off
	v_lshl_add_u64 v[2:3], v[2:3], 0, s[50:51]
	global_load_dword v12, v[2:3], off
	v_lshl_add_u64 v[2:3], v[2:3], 0, s[50:51]
	global_load_dword v13, v[2:3], off
	v_lshl_add_u64 v[2:3], v[2:3], 0, s[50:51]
	global_load_dword v14, v[2:3], off
	v_lshl_add_u64 v[2:3], v[2:3], 0, s[50:51]
	global_load_dword v15, v[2:3], off
	v_lshl_add_u64 v[2:3], v[2:3], 0, s[50:51]
	global_load_dword v16, v[2:3], off
	v_lshl_add_u64 v[2:3], v[2:3], 0, s[50:51]
	global_load_dword v17, v[2:3], off
	v_lshl_add_u64 v[2:3], v[2:3], 0, s[50:51]
	global_load_dword v18, v[2:3], off
	v_lshl_add_u64 v[2:3], v[2:3], 0, s[50:51]
	global_load_dword v19, v[2:3], off
	v_or_b32_e32 v20, s9, v93
	s_movk_i32 s9, 0x104
	v_mad_u32_u24 v20, v20, s9, v95
	v_lshl_add_u64 v[2:3], v[2:3], 0, s[50:51]
	s_movk_i32 s9, 0x80
	s_and_b64 vcc, exec, s[6:7]
	s_mov_b64 s[6:7], 0
	s_waitcnt vmcnt(0)
	ds_write_b32 v20, v4
	ds_write_b32 v20, v5 offset:2080
	ds_write_b32 v20, v6 offset:4160
	ds_write_b32 v20, v7 offset:6240
	ds_write_b32 v20, v8 offset:8320
	ds_write_b32 v20, v9 offset:10400
	ds_write_b32 v20, v10 offset:12480
	ds_write_b32 v20, v11 offset:14560
	ds_write_b32 v20, v12 offset:16640
	ds_write_b32 v20, v13 offset:18720
	ds_write_b32 v20, v14 offset:20800
	ds_write_b32 v20, v15 offset:22880
	ds_write_b32 v20, v16 offset:24960
	ds_write_b32 v20, v17 offset:27040
	ds_write_b32 v20, v18 offset:29120
	ds_write_b32 v20, v19 offset:31200
	s_cbranch_vccnz .LBB0_326
	s_waitcnt lgkmcnt(0)
	s_barrier
	ds_read2_b32 v[8:9], v99 offset1:32
	v_add_u32_e32 v2, 0x400, v100
	ds_read2_b32 v[10:11], v2 offset0:4 offset1:36
	ds_read2_b32 v[12:13], v99 offset0:65 offset1:97
	ds_read2_b32 v[14:15], v2 offset0:69 offset1:101
	ds_read2_b32 v[16:17], v99 offset0:130 offset1:162
	ds_read2_b32 v[18:19], v2 offset0:134 offset1:166
	ds_read2_b32 v[20:21], v99 offset0:195 offset1:227
	ds_read2_b32 v[22:23], v2 offset0:199 offset1:231
	s_lshl_b32 s6, s8, 1
	s_add_u32 s4, s4, s6
	s_addc_u32 s5, s5, 0
	v_mov_b32_e32 v85, v73
	s_waitcnt lgkmcnt(5)
	v_cvt_pk_bf16_f32 v2, v8, v12
	v_or_b32_e32 v8, s18, v97
	v_lshl_add_u64 v[6:7], s[4:5], 0, v[84:85]
	v_mul_u32_u24_e32 v72, s27, v8
	s_waitcnt lgkmcnt(1)
	v_cvt_pk_bf16_f32 v3, v16, v20
	v_cvt_pk_bf16_f32 v4, v10, v14
	s_waitcnt lgkmcnt(0)
	v_cvt_pk_bf16_f32 v5, v18, v22
	v_lshl_add_u64 v[24:25], v[72:73], 1, v[6:7]
	global_store_dwordx4 v[24:25], v[2:5], off sc1
	v_add_u32_e32 v8, 0x400, v103
	ds_read2_b32 v[2:3], v102 offset1:65
	ds_read2_b32 v[4:5], v8 offset0:4 offset1:69
	ds_read2_b32 v[24:25], v102 offset0:130 offset1:195
	ds_read2_b32 v[26:27], v8 offset0:134 offset1:199
	v_or_b32_e32 v8, s18, v101
	v_mul_u32_u24_e32 v72, s27, v8
	v_or_b32_e32 v8, s18, v104
	s_waitcnt lgkmcnt(3)
	v_cvt_pk_bf16_f32 v2, v2, v3
	s_waitcnt lgkmcnt(1)
	v_cvt_pk_bf16_f32 v3, v24, v25
	v_cvt_pk_bf16_f32 v4, v4, v5
	s_waitcnt lgkmcnt(0)
	v_cvt_pk_bf16_f32 v5, v26, v27
	v_lshl_add_u64 v[24:25], v[72:73], 1, v[6:7]
	v_mul_u32_u24_e32 v72, s27, v8
	global_store_dwordx4 v[24:25], v[2:5], off sc1
	v_add_u32_e32 v10, 0x400, v107
	s_nop 0
	v_cvt_pk_bf16_f32 v2, v9, v13
	v_cvt_pk_bf16_f32 v3, v17, v21
	v_cvt_pk_bf16_f32 v4, v11, v15
	v_cvt_pk_bf16_f32 v5, v19, v23
	v_lshl_add_u64 v[8:9], v[72:73], 1, v[6:7]
	global_store_dwordx4 v[8:9], v[2:5], off sc1
	ds_read2_b32 v[2:3], v106 offset1:65
	ds_read2_b32 v[4:5], v10 offset0:4 offset1:69
	ds_read2_b32 v[8:9], v106 offset0:130 offset1:195
	ds_read2_b32 v[10:11], v10 offset0:134 offset1:199
	s_waitcnt lgkmcnt(2)
	v_cvt_pk_bf16_f32 v4, v4, v5
	v_cvt_pk_bf16_f32 v2, v2, v3
	s_waitcnt lgkmcnt(1)
	v_cvt_pk_bf16_f32 v3, v8, v9
	v_add_u32_e32 v8, s18, v105
	v_mul_hi_u32_u24_e32 v9, s27, v8
	v_mul_u32_u24_e32 v8, s27, v8
	s_waitcnt lgkmcnt(0)
	v_cvt_pk_bf16_f32 v5, v10, v11
	v_lshl_add_u64 v[6:7], v[8:9], 1, v[6:7]
	global_store_dwordx4 v[6:7], v[2:5], off sc1
	s_barrier

.LBB0_341:
	v_add_u32_e32 v6, s4, v114
	v_pk_mul_f32 v[12:13], v[10:11], v[4:5] op_sel:[0,1] op_sel_hi:[1,0]
	ds_write_b64 v6, v[4:5] offset:264
	v_pk_mul_f32 v[6:7], v[8:9], v[4:5]
	v_pk_fma_f32 v[4:5], v[8:9], v[4:5], v[12:13]
	s_add_i32 s4, s4, 8
	s_cmp_eq_u32 s4, 0
	v_sub_f32_e32 v4, v6, v12
	s_cbranch_scc0 .LBB0_341
	s_cmp_eq_u32 s18, 0
	s_cbranch_scc0 .LBB0_344
	ds_read_b64 v[4:5], v122 offset:17152
	v_lshl_add_u64 v[2:3], v[2:3], 3, s[54:55]
	s_waitcnt lgkmcnt(0)
	global_store_dwordx2 v[2:3], v[4:5], off sc1

.LBB0_354:
	s_or_b64 exec, exec, s[4:5]
	s_waitcnt lgkmcnt(1)
	v_cvt_pk_bf16_f32 v2, v2, v3
	v_cvt_pk_bf16_f32 v3, v4, v5
	s_waitcnt lgkmcnt(0)
	v_cvt_pk_bf16_f32 v4, v6, v7
	v_lshl_add_u32 v6, v11, 4, s18
	v_cvt_pk_bf16_f32 v5, v8, v9
	v_or_b32_e32 v8, v6, v12
	v_mov_b64_e32 v[6:7], s[52:53]
	s_movk_i32 s4, 0x500
	v_mad_i64_i32 v[6:7], s[4:5], v8, s4, v[6:7]
	v_lshlrev_b32_e32 v72, 1, v10
	s_addk_i32 s19, 0x200
	v_lshl_add_u64 v[6:7], v[6:7], 0, v[72:73]
	s_cmpk_eq_i32 s19, 0x2800
	global_store_dwordx4 v[6:7], v[2:5], off sc1
	s_cbranch_scc1 .LBB0_360

.LBB0_361:
	s_nop 0
	v_add_u32_e32 v2, s4, v6
	v_and_b32_e32 v3, 63, v2
	s_movk_i32 s5, 0x108
	v_mad_u32_u24 v28, v3, s5, v111
	v_lshl_add_u32 v16, v3, 7, v112
	v_cmp_lt_u32_e32 vcc, 63, v2
	ds_read_b128 v[2:5], v16 offset:512
	ds_read_b128 v[8:11], v16 offset:528
	ds_read_b128 v[12:15], v16 offset:544
	ds_read_b128 v[16:19], v16 offset:560
	ds_read_b64 v[28:29], v28 offset:16896
	s_waitcnt lgkmcnt(4)
	v_mov_b32_e32 v30, v5
	v_mov_b32_e32 v31, v2
	v_mov_b32_e32 v20, v3
	v_mov_b32_e32 v21, v4
	s_waitcnt lgkmcnt(0)
	v_pk_mul_f32 v[30:31], v[28:29], v[30:31]
	v_mov_b32_e32 v23, v10
	v_pk_fma_f32 v[20:21], v[28:29], v[20:21], v[30:31] op_sel:[0,0,1] op_sel_hi:[1,1,0]
	v_mov_b32_e32 v31, v4
	v_mov_b32_e32 v4, v3
	v_mov_b32_e32 v30, v2
	v_pk_mul_f32 v[2:3], v[28:29], v[4:5] op_sel:[1,0]
	v_mov_b32_e32 v5, v10
	v_pk_fma_f32 v[2:3], v[28:29], v[30:31], v[2:3] op_sel_hi:[0,1,1] neg_lo:[0,0,1] neg_hi:[0,0,1]
	v_cndmask_b32_e32 v21, v3, v21, vcc
	v_cndmask_b32_e32 v20, v2, v20, vcc
	v_mov_b32_e32 v2, v11
	v_mov_b32_e32 v3, v8
	v_mov_b32_e32 v10, v9
	v_mov_b32_e32 v22, v9
	v_pk_mul_f32 v[2:3], v[28:29], v[2:3]
	v_mov_b32_e32 v4, v8
	v_pk_mul_f32 v[8:9], v[28:29], v[10:11] op_sel:[1,0]
	v_pk_fma_f32 v[2:3], v[28:29], v[22:23], v[2:3] op_sel:[0,0,1] op_sel_hi:[1,1,0]
	v_pk_fma_f32 v[4:5], v[28:29], v[4:5], v[8:9] op_sel_hi:[0,1,1] neg_lo:[0,0,1] neg_hi:[0,0,1]
	v_mov_b32_e32 v25, v14
	v_cndmask_b32_e32 v10, v5, v3, vcc
	v_cndmask_b32_e32 v11, v4, v2, vcc
	v_mov_b32_e32 v2, v15
	v_mov_b32_e32 v3, v12
	v_mov_b32_e32 v5, v14
	v_mov_b32_e32 v14, v13
	v_mov_b32_e32 v24, v13
	v_pk_mul_f32 v[2:3], v[28:29], v[2:3]
	v_mov_b32_e32 v4, v12
	v_pk_mul_f32 v[8:9], v[28:29], v[14:15] op_sel:[1,0]
	v_pk_fma_f32 v[2:3], v[28:29], v[24:25], v[2:3] op_sel:[0,0,1] op_sel_hi:[1,1,0]
	v_pk_fma_f32 v[4:5], v[28:29], v[4:5], v[8:9] op_sel_hi:[0,1,1] neg_lo:[0,0,1] neg_hi:[0,0,1]
	v_mov_b32_e32 v27, v18
	v_cndmask_b32_e32 v12, v5, v3, vcc
	v_cndmask_b32_e32 v13, v4, v2, vcc
	v_mov_b32_e32 v2, v19
	v_mov_b32_e32 v3, v16
	v_mov_b32_e32 v5, v18
	v_mov_b32_e32 v18, v17
	v_mov_b32_e32 v26, v17
	v_pk_mul_f32 v[2:3], v[28:29], v[2:3]
	v_mov_b32_e32 v4, v16
	v_pk_mul_f32 v[8:9], v[28:29], v[18:19] op_sel:[1,0]
	v_pk_fma_f32 v[2:3], v[28:29], v[26:27], v[2:3] op_sel:[0,0,1] op_sel_hi:[1,1,0]
	v_pk_fma_f32 v[4:5], v[28:29], v[4:5], v[8:9] op_sel_hi:[0,1,1] neg_lo:[0,0,1] neg_hi:[0,0,1]
	v_cndmask_b32_e32 v5, v5, v3, vcc
	v_cndmask_b32_e32 v8, v4, v2, vcc
	v_cvt_pk_bf16_f32 v5, v8, v5
	v_add_u32_e32 v8, s4, v7
	v_ashrrev_i32_e32 v9, 31, v8
	v_lshlrev_b64 v[8:9], 10, v[8:9]
	s_add_i32 s4, s4, 8
	v_cvt_pk_bf16_f32 v2, v20, v21
	v_cvt_pk_bf16_f32 v3, v11, v10
	v_cvt_pk_bf16_f32 v4, v13, v12
	v_lshl_add_u64 v[8:9], v[78:79], 0, v[8:9]
	s_cmp_lg_u32 s4, 32
	global_store_dwordx4 v[8:9], v[2:5], off sc1
	s_cbranch_scc1 .LBB0_361
	s_barrier
	s_branch .LBB0_277
.LBB0_363:
	s_waitcnt vmcnt(0)
	s_barrier
	v_and_b32_e32 v1, 0x3ff, v0
	v_cmp_eq_u32_e32 vcc, 0, v1
	s_and_saveexec_b64 s[4:5], vcc
	s_cbranch_execz .Lmg_z1
	v_mov_b32_e32 v1, 0xe818000
	v_mov_b32_e32 v2, 1
	global_atomic_add v1, v2, s[78:79]
.Lmg_z1:
	s_or_b64 exec, exec, s[4:5]
	v_readlane_b32 s26, v254, 38
	v_readlane_b32 s36, v254, 40
	v_readlane_b32 s96, v254, 37
	v_readlane_b32 s27, v254, 39
	v_readlane_b32 s37, v254, 41

.LBB0_414:
	s_cmp_lt_i32 s26, 4
	s_cselect_b64 s[92:93], -1, 0
	s_and_b64 s[0:1], s[92:93], s[0:1]
	s_andn2_b64 vcc, exec, s[0:1]
	s_cbranch_vccnz .LBB0_539
	s_add_i32 s96, s96, 0xffffffc0
	s_cmpk_gt_i32 s3, 0xff
	s_cselect_b64 s[0:1], -1, 0
	s_cmpk_lt_i32 s3, 0x100
	s_cselect_b64 s[4:5], -1, 0
	s_and_b64 s[6:7], s[4:5], exec
	s_cselect_b32 s2, 0, 0x80
	s_cmp_ge_i32 s96, s2
	s_cselect_b64 s[6:7], -1, 0
	s_and_b64 s[0:1], s[0:1], s[6:7]
	s_and_b64 vcc, exec, s[0:1]
	s_cbranch_vccnz .LBB0_436
	v_and_b32_e32 v10, 0x3ff, v0
	s_cmpk_gt_u32 s96, 0x7f
	v_readfirstlane_b32 s1, v10
	s_cbranch_scc1 .LBB0_436
	v_cmp_eq_u32_e32 vcc, 0, v10
	s_and_saveexec_b64 s[6:7], vcc
	s_cbranch_execz .Lmg_s2
	s_lshl_b32 s8, s96, 2
	s_and_b32 s8, s8, 28
	s_bfe_u32 s9, s96, 0x20005
	s_or_b32 s8, s8, s9
	s_lshl_b32 s8, s8, 8
	s_add_u32 s8, s78, s8
	s_addc_u32 s9, s79, 0
	v_mov_b32_e32 v2, 0xe814000
	s_mov_b32 s10, 0x40000
.Lmg_s0:
	global_load_dword v3, v2, s[8:9] sc1
	s_waitcnt vmcnt(0)
	v_cmp_ne_u32_e32 vcc, 0, v3
	s_cbranch_vccnz .Lmg_s1
	s_sleep 1
	s_sub_u32 s10, s10, 1
	s_cmp_lg_u32 s10, 0
	s_cbranch_scc1 .Lmg_s0

.Lmg_s2:
	s_or_b64 exec, exec, s[6:7]
	s_barrier
	v_lshrrev_b32_e32 v1, 5, v10
	v_lshrrev_b32_e32 v12, 1, v10
	v_and_b32_e32 v1, 4, v1
	v_bfe_u32 v2, v10, 2, 2
	v_and_b32_e32 v11, 24, v12
	v_or3_b32 v1, v1, v2, v11
	v_lshlrev_b32_e32 v2, 4, v10
	v_add_u32_e32 v3, 0x2000, v2
	v_and_b32_e32 v5, 32, v10
	v_lshrrev_b32_e32 v3, 7, v3
	s_movk_i32 s6, 0xe0
	v_bitop3_b32 v13, v2, v5, 48 bitop3:0x6c
	v_and_b32_e32 v14, 64, v10
	v_and_or_b32 v4, v3, s6, v1
	v_or_b32_e32 v2, v13, v14
	v_mul_u32_u24_e32 v4, 0x280, v4
	v_lshrrev_b32_e32 v2, 1, v2
	v_or_b32_e32 v4, v4, v2
	v_lshlrev_b32_e32 v130, 1, v4
	v_bfe_u32 v4, v10, 2, 4
	s_movk_i32 s6, 0xf0
	v_and_or_b32 v3, v3, s6, v4
	v_mul_u32_u24_e32 v15, 0x280, v3
	v_or_b32_e32 v3, v15, v2
	v_lshlrev_b32_e32 v132, 1, v3
	v_lshrrev_b32_e32 v3, 3, v10
	s_movk_i32 s6, 0x60
	v_and_or_b32 v1, v3, s6, v1
	v_mul_u32_u24_e32 v1, 0x280, v1
	s_add_u32 s18, s78, 0x1600000
	v_or_b32_e32 v1, v1, v2
	s_movk_i32 s6, 0x70
	s_addc_u32 s19, s79, 0
	v_lshlrev_b32_e32 v134, 1, v1
	v_and_or_b32 v1, v3, s6, v4
	s_lshr_b32 s6, s96, 4
	s_lshl_b32 s7, s96, 3
	s_and_b32 s7, s7, 56
	s_and_b32 s6, s6, 6
	s_or_b32 s6, s7, s6
	s_bfe_u32 s7, s96, 0x10004
	s_or_b32 s81, s6, s7
	s_bfe_u32 s7, s96, 0x10003
	s_lshr_b32 s8, s1, 6
	s_or_b32 s82, s6, s7
	s_lshr_b32 s10, s1, 8
	s_lshl_b32 s0, s8, 10
	s_mul_i32 s6, s82, 0x50000
	s_add_u32 s22, s18, s6
	s_addc_u32 s23, s19, 0
	s_add_i32 s24, s0, 0
	s_add_i32 m0, s24, 0x10000
	s_mul_i32 s9, s81, 0x50000
	global_load_lds_dwordx4 v134, s[22:23]
	s_add_i32 m0, s24, 0x12000
	s_add_u32 s6, s22, 0x28000
	global_load_lds_dwordx4 v130, s[22:23]
	s_addc_u32 s7, s23, 0
	s_add_i32 m0, s24, 0x14000
	v_mul_u32_u24_e32 v16, 0x280, v1
	global_load_lds_dwordx4 v134, s[6:7]
	s_add_i32 m0, s24, 0x16000
	s_add_u32 s20, s28, s9
	v_or_b32_e32 v1, v2, v16
	s_addc_u32 s21, s29, 0
	s_add_i32 s25, s24, 0x2000
	v_lshlrev_b32_e32 v136, 1, v1
	global_load_lds_dwordx4 v130, s[6:7]
	s_mov_b32 m0, s24
	s_add_u32 s6, s20, 0x28000
	global_load_lds_dwordx4 v136, s[20:21]
	s_mov_b32 m0, s25
	s_addc_u32 s7, s21, 0
	s_add_i32 s26, s24, 0x4000
	global_load_lds_dwordx4 v132, s[20:21]
	s_mov_b32 m0, s26
	s_add_i32 s27, s24, 0x6000
	global_load_lds_dwordx4 v136, s[6:7]
	s_mov_b32 m0, s27
	v_mov_b32_e32 v139, 0
	global_load_lds_dwordx4 v132, s[6:7]
	v_mov_b32_e32 v135, v139
	v_mov_b32_e32 v131, v139
	v_mov_b32_e32 v137, v139
	v_mov_b32_e32 v133, v139
	s_cmp_eq_u32 s10, 1
	s_mov_b32 s34, 0
	v_lshl_add_u64 v[8:9], s[22:23], 0, v[134:135]
	v_lshl_add_u64 v[6:7], s[22:23], 0, v[130:131]
	v_lshl_add_u64 v[2:3], s[20:21], 0, v[136:137]
	s_cselect_b64 s[6:7], -1, 0
	s_cmp_lg_u32 s10, 1
	v_lshl_add_u64 v[4:5], s[20:21], 0, v[132:133]
	s_cbranch_scc1 .LBB0_419
	s_barrier

.LBB0_436:
	v_readlane_b32 s96, v254, 37
	s_nop 3
	s_add_i32 s0, s96, 0xffffffc0
	s_cmp_lt_u32 s0, 0x80
	s_cbranch_scc1 .LBB0_539
	v_and_b32_e32 v2, 0x3ff, v0
	v_cmp_eq_u32_e32 vcc, 0, v2
	s_and_saveexec_b64 s[6:7], vcc
	s_cbranch_execz .Lmg_p2
	v_mov_b32_e32 v2, 0xe818000
	s_mov_b32 s10, 0x40000
.Lmg_p0:
	global_load_dword v3, v2, s[78:79] sc1
	s_waitcnt vmcnt(0)
	v_cmp_le_u32_e32 vcc, 0xc0, v3
	s_cbranch_vccnz .Lmg_p1
	s_sleep 1
	s_sub_u32 s10, s10, 1
	s_cmp_lg_u32 s10, 0
	s_cbranch_scc1 .Lmg_p0

.Lmg_p2:
	s_or_b64 exec, exec, s[6:7]
	s_barrier
	s_add_u32 s12, s78, 0x580000
	s_addc_u32 s13, s79, 0
	s_and_b64 s[0:1], s[4:5], exec
	s_cselect_b32 s0, 0, 0xffffff80
	s_add_i32 s2, s0, s3
	s_add_i32 s24, s0, s96
	s_cmp_lt_u32 s96, 64
	s_cselect_b32 s24, s96, s24
	v_and_b32_e32 v1, 0x3ff, v0
	v_bfe_u32 v142, v0, 5, 5
	v_readfirstlane_b32 s0, v1
	s_cmpk_gt_u32 s24, 0xff
	v_lshlrev_b32_e32 v143, 4, v1
	s_cbranch_scc1 .LBB0_457
	v_lshrrev_b32_e32 v4, 1, v1
	v_and_b32_e32 v2, 4, v142
	v_bfe_u32 v3, v1, 2, 2
	v_and_b32_e32 v10, 24, v4
	v_or3_b32 v2, v2, v3, v10
	v_add_u32_e32 v3, 0x2000, v143
	v_and_b32_e32 v5, 32, v1
	v_lshrrev_b32_e32 v3, 7, v3
	s_movk_i32 s4, 0xe0
	v_bitop3_b32 v5, v143, v5, 48 bitop3:0x6c
	v_and_or_b32 v4, v3, s4, v2
	v_and_or_b32 v5, v1, 64, v5
	v_lshl_or_b32 v130, v4, 9, v5
	v_bfe_u32 v4, v1, 2, 4
	s_movk_i32 s4, 0xf0
	v_and_or_b32 v3, v3, s4, v4
	v_lshl_or_b32 v132, v3, 9, v5
	v_lshrrev_b32_e32 v3, 3, v1
	s_movk_i32 s4, 0x60
	s_add_u32 s25, s78, 0x3200000
	v_and_or_b32 v2, v3, s4, v2
	s_movk_i32 s4, 0x70
	s_addc_u32 s26, s79, 0
	v_lshl_or_b32 v134, v2, 9, v5
	v_and_or_b32 v2, v3, s4, v4
	s_lshl_b32 s4, s96, 3
	s_and_b32 s4, s4, 56
	s_bfe_u32 s5, s24, 0x30003
	s_lshr_b32 s8, s0, 6
	s_or_b32 s91, s4, s5
	s_bfe_u32 s6, s24, 0x50006
	s_lshr_b32 s1, s0, 8
	s_lshl_b32 s27, s8, 10
	s_lshl_b32 s7, s91, 17
	s_lshl_b32 s4, s6, 17
	s_add_u32 s22, s12, s4
	s_addc_u32 s23, s13, 0
	s_add_i32 s80, s27, 0
	s_add_i32 m0, s80, 0x10000
	v_lshl_or_b32 v136, v2, 9, v5
	global_load_lds_dwordx4 v134, s[22:23]
	s_add_i32 m0, s80, 0x12000
	s_add_u32 s4, s22, 0x10000
	global_load_lds_dwordx4 v130, s[22:23]
	s_addc_u32 s5, s23, 0
	s_add_i32 m0, s80, 0x14000
	v_mov_b32_e32 v135, 0
	global_load_lds_dwordx4 v134, s[4:5]
	s_add_i32 m0, s80, 0x16000
	s_add_u32 s28, s25, s7
	s_addc_u32 s29, s26, 0
	s_add_i32 s82, s80, 0x2000
	global_load_lds_dwordx4 v130, s[4:5]
	s_mov_b32 m0, s80
	s_add_u32 s4, s28, 0x10000
	global_load_lds_dwordx4 v136, s[28:29]
	s_mov_b32 m0, s82
	s_addc_u32 s5, s29, 0
	s_add_i32 s83, s80, 0x4000
	global_load_lds_dwordx4 v132, s[28:29]
	s_mov_b32 m0, s83
	s_add_i32 s84, s80, 0x6000
	global_load_lds_dwordx4 v136, s[4:5]
	s_mov_b32 m0, s84
	v_mov_b32_e32 v131, v135
	global_load_lds_dwordx4 v132, s[4:5]
	v_mov_b32_e32 v137, v135
	v_mov_b32_e32 v133, v135
	s_cmp_eq_u32 s1, 1
	s_mov_b64 s[36:37], s[92:93]
	v_lshl_add_u64 v[8:9], s[22:23], 0, v[134:135]
	v_lshl_add_u64 v[6:7], s[22:23], 0, v[130:131]
	v_lshl_add_u64 v[2:3], s[28:29], 0, v[136:137]
	s_cselect_b64 s[4:5], -1, 0
	s_cmp_lg_u32 s1, 1
	v_lshl_add_u64 v[4:5], s[28:29], 0, v[132:133]
	s_cbranch_scc1 .LBB0_440
	s_barrier
